# row-statistics exchange without the arrival counter: slots preset to -1.0 at kernel start, wave 0 polls the panel's 256x4 slots directly (dwordx4 per row) and writes the 256 rstd values; store-ack wai
# speedup vs baseline: 1.0107x; 1.0008x over previous
; #define LAS __attribute__((address_space(3)))
; #define KARGS() const CAS Args* KA = kargs()
; __global__ void __launch_bounds__(512, 2) mega_fwd(Args a) {
;     extern __shared__ __attribute__((aligned(16))) unsigned char lds_raw[];
;     LAS unsigned char* lds = (LAS unsigned char*)lds_raw;
;     cg::grid_group grid = cg::this_grid();
;     if (threadIdx.x < 16) ((LAS unsigned*)(lds + 131072))[threadIdx.x] = 0u;
;     __syncthreads();
;     XcdBarrier xbar; { KARGS(); xbar = xcd_barrier_post((unsigned*)(KA->ws + WS_BAR), (volatile LAS unsigned*)(lds + 131072)); }
_Z8mega_fwd4Args:
	s_add_u32 s4, s0, 0xc0
	v_and_b32_e32 v195, 0x3ff, v0
	s_addc_u32 s5, s1, 0
	v_cmp_gt_u32_e32 vcc, 16, v195
	s_and_saveexec_b64 s[6:7], vcc
	v_lshl_add_u32 v1, v195, 2, 0
	v_add_u32_e32 v1, 0x20000, v1
	v_mov_b32_e32 v2, 0
	ds_write_b32 v1, v2
	s_or_b64 exec, exec, s[6:7]
	s_mov_b64 s[6:7], s[0:1]
	s_load_dwordx2 s[28:29], s[0:1], 0xc0
	s_waitcnt lgkmcnt(0)
	s_barrier
	s_load_dwordx2 s[90:91], s[6:7], 0xb8
	s_getreg_b32 s3, hwreg(HW_REG_XCC_ID, 0, 4)
	v_cmp_eq_u32_e64 s[8:9], 0, v195
	s_waitcnt lgkmcnt(0)
	s_add_u32 s46, s90, 0x1900000
	s_addc_u32 s47, s91, 0
	v_mov_b32_e32 v200, s2
	v_lshl_add_u32 v200, v200, 9, v195
	v_lshlrev_b32_e32 v200, 2, v200
	v_mov_b32_e32 v201, 0xbf800000
	global_store_dword v200, v201, s[46:47]
	s_add_u32 s46, s46, 0x80000
	s_addc_u32 s47, s47, 0
	global_store_dword v200, v201, s[46:47]
	s_add_u32 s46, s46, 0x80000
	s_addc_u32 s47, s47, 0
	global_store_dword v200, v201, s[46:47]
	s_add_u32 s6, s90, 0x32000
	s_addc_u32 s7, s91, 0
	v_writelane_b32 v255, s6, 0
	s_and_b32 s3, s3, 15
	s_nop 0
	v_writelane_b32 v255, s7, 1
	v_writelane_b32 v255, s3, 2
	s_mov_b64 s[6:7], exec
	v_writelane_b32 v255, s8, 3
	s_nop 1
	v_writelane_b32 v255, s9, 4
	s_and_b64 s[8:9], s[6:7], s[8:9]
	s_mov_b64 exec, s[8:9]
	s_cbranch_execz .LBB0_5
	s_mov_b64 s[8:9], exec
	v_mbcnt_lo_u32_b32 v1, s8, 0
	v_mbcnt_hi_u32_b32 v1, s9, v1
	v_cmp_eq_u32_e32 vcc, 0, v1
	s_and_b64 s[10:11], exec, vcc
	s_mov_b64 exec, s[10:11]
	s_cbranch_execz .LBB0_5
	v_readlane_b32 s3, v255, 2
	s_bcnt1_i32_b64 s8, s[8:9]
	s_lshl_b32 s3, s3, 8
	v_mov_b32_e32 v2, s8
	v_readlane_b32 s8, v255, 0
	v_mov_b32_e32 v1, s3
	v_readlane_b32 s9, v255, 1
	s_nop 4
	global_atomic_add v1, v2, s[8:9] offset:1024

;     __device__ __forceinline__ void run(const f32x4 (&v)[2][2][4][2], const Unit& u, int wr, int wc, int fr, int fq, PG8_LAS unsigned char* lds, int wid, int lane) const {
;     ...
;         const int row = wid * 32 + (lane & 31);
;         if (lane < 32) {
;             const float tot = (P[row * 4 + 0] + P[row * 4 + 1]) + (P[row * 4 + 2] + P[row * 4 + 3]);
;             __hip_atomic_store(xbuf + ((size_t)(pmg * BM + row) * 4 + u.pn), tot, __ATOMIC_RELAXED, __HIP_MEMORY_SCOPE_AGENT);
;         }
;         asm volatile("s_waitcnt vmcnt(0)" ::: "memory");
;         if (lane == 0) __hip_atomic_fetch_add(cnt + 64 * pmg, 1u, __ATOMIC_RELAXED, __HIP_MEMORY_SCOPE_AGENT);
;         if (wid == 0) {
;             unsigned sp = 0;
;             while ((unsigned)__builtin_amdgcn_readfirstlane(__hip_atomic_load(cnt + 64 * pmg, __ATOMIC_RELAXED, __HIP_MEMORY_SCOPE_AGENT)) < 32u) { __builtin_amdgcn_s_sleep(2); if (++sp > (1u << 22)) break; }
;             __builtin_amdgcn_fence(__ATOMIC_ACQUIRE, "agent");
;         }
;         asm volatile("s_waitcnt vmcnt(0) lgkmcnt(0)" ::: "memory"); __builtin_amdgcn_s_barrier(); asm volatile("" ::: "memory");
;         if (lane < 32) {
;             const float* slot = xbuf + (size_t)(pmg * BM + row) * 4; float t = 0.f;
; #pragma unroll
;             for (int k = 0; k < 4; ++k) t += __hip_atomic_load(slot + k, __ATOMIC_RELAXED, __HIP_MEMORY_SCOPE_AGENT);
;             S[row] = rsqrtf(t * (1.0f / 1024.0f) + eps);
;         }
.LBB0_775:
	s_or_b64 exec, exec, s[10:11]
	v_lshl_add_u32 v152, v129, 2, 0
	s_mov_b64 s[54:55], exec
	s_cmp_lt_u32 s36, 64
	s_cselect_b64 s[50:51], -1, 0
	s_cmp_gt_u32 s36, 63
	s_cbranch_scc1 .LBB0_790
	s_lshl_b32 s26, s59, 8
	v_add_u32_e32 v204, s26, v195
	v_ashrrev_i32_e32 v205, 31, v204
	v_lshl_add_u64 v[204:205], v[204:205], 4, s[52:53]
	v_lshlrev_b32_e32 v206, 2, v195
	s_mov_b32 s26, 0x40000
.Lpss_a0_poll:
	global_load_dwordx4 v[128:131], v[204:205], off offset:0 sc1
	global_load_dwordx4 v[132:135], v[204:205], off offset:1024 sc1
	s_waitcnt vmcnt(0)
	v_min3_f32 v207, v128, v129, v130
	v_min3_f32 v207, v207, v131, v132
	v_min3_f32 v207, v207, v133, v134
	v_min_f32_e32 v207, v207, v135
	v_cmp_gt_f32_e32 vcc, 0, v207
	s_cbranch_vccz .Lpss_a0_ok
	s_sleep 1
	s_sub_u32 s26, s26, 1
	s_cmp_lg_u32 s26, 0
	s_cbranch_scc1 .Lpss_a0_poll
.Lpss_a0_ok:
	v_add_f32_e32 v128, 0, v128
	v_add_f32_e32 v128, v128, v129
	v_add_f32_e32 v128, v128, v130
	v_add_f32_e32 v128, v128, v131
	v_fmamk_f32 v128, v128, 0x3a800000, v184
	v_mul_f32_e32 v129, 0x4b800000, v128
	v_cmp_gt_f32_e32 vcc, s67, v128
	s_nop 1
	v_cndmask_b32_e32 v128, v128, v129, vcc
	v_rsq_f32_e32 v128, v128
	s_nop 0
	v_mul_f32_e32 v129, 0x45800000, v128
	v_cndmask_b32_e32 v128, v128, v129, vcc
	ds_write_b32 v206, v128 offset:4096
	v_add_f32_e32 v132, 0, v132
	v_add_f32_e32 v132, v132, v133
	v_add_f32_e32 v132, v132, v134
	v_add_f32_e32 v132, v132, v135
	v_fmamk_f32 v132, v132, 0x3a800000, v184
	v_mul_f32_e32 v133, 0x4b800000, v132
	v_cmp_gt_f32_e32 vcc, s67, v132
	s_nop 1
	v_cndmask_b32_e32 v132, v132, v133, vcc
	v_rsq_f32_e32 v132, v132
	s_nop 0
	v_mul_f32_e32 v133, 0x45800000, v132
	v_cndmask_b32_e32 v132, v132, v133, vcc
	ds_write_b32 v206, v132 offset:4352
	s_mov_b32 s26, 0x40000
.Lpss_a1_poll:
	global_load_dwordx4 v[128:131], v[204:205], off offset:2048 sc1
	global_load_dwordx4 v[132:135], v[204:205], off offset:3072 sc1
	s_waitcnt vmcnt(0)
	v_min3_f32 v207, v128, v129, v130
	v_min3_f32 v207, v207, v131, v132
	v_min3_f32 v207, v207, v133, v134
	v_min_f32_e32 v207, v207, v135
	v_cmp_gt_f32_e32 vcc, 0, v207
	s_cbranch_vccz .Lpss_a1_ok
	s_sleep 1
	s_sub_u32 s26, s26, 1
	s_cmp_lg_u32 s26, 0
	s_cbranch_scc1 .Lpss_a1_poll
.Lpss_a1_ok:
	v_add_f32_e32 v128, 0, v128
	v_add_f32_e32 v128, v128, v129
	v_add_f32_e32 v128, v128, v130
	v_add_f32_e32 v128, v128, v131
	v_fmamk_f32 v128, v128, 0x3a800000, v184
	v_mul_f32_e32 v129, 0x4b800000, v128
	v_cmp_gt_f32_e32 vcc, s67, v128
	s_nop 1
	v_cndmask_b32_e32 v128, v128, v129, vcc
	v_rsq_f32_e32 v128, v128
	s_nop 0
	v_mul_f32_e32 v129, 0x45800000, v128
	v_cndmask_b32_e32 v128, v128, v129, vcc
	ds_write_b32 v206, v128 offset:4608
	v_add_f32_e32 v132, 0, v132
	v_add_f32_e32 v132, v132, v133
	v_add_f32_e32 v132, v132, v134
	v_add_f32_e32 v132, v132, v135
	v_fmamk_f32 v132, v132, 0x3a800000, v184
	v_mul_f32_e32 v133, 0x4b800000, v132
	v_cmp_gt_f32_e32 vcc, s67, v132
	s_nop 1
	v_cndmask_b32_e32 v132, v132, v133, vcc
	v_rsq_f32_e32 v132, v132
	s_nop 0
	v_mul_f32_e32 v133, 0x45800000, v132
	v_cndmask_b32_e32 v132, v132, v133, vcc
	ds_write_b32 v206, v132 offset:4864

;     __device__ __forceinline__ void run(const f32x4 (&v)[2][2][4][2], const Unit& u, int wr, int wc, int fr, int fq, PG8_LAS unsigned char* lds, int wid, int lane) const {
;     ...
;         const int row = wid * 32 + (lane & 31);
;         if (lane < 32) {
;             const float tot = (P[row * 4 + 0] + P[row * 4 + 1]) + (P[row * 4 + 2] + P[row * 4 + 3]);
;             __hip_atomic_store(xbuf + ((size_t)(pmg * BM + row) * 4 + u.pn), tot, __ATOMIC_RELAXED, __HIP_MEMORY_SCOPE_AGENT);
;         }
;         asm volatile("s_waitcnt vmcnt(0)" ::: "memory");
;         if (lane == 0) __hip_atomic_fetch_add(cnt + 64 * pmg, 1u, __ATOMIC_RELAXED, __HIP_MEMORY_SCOPE_AGENT);
;         if (wid == 0) {
;             unsigned sp = 0;
;             while ((unsigned)__builtin_amdgcn_readfirstlane(__hip_atomic_load(cnt + 64 * pmg, __ATOMIC_RELAXED, __HIP_MEMORY_SCOPE_AGENT)) < 32u) { __builtin_amdgcn_s_sleep(2); if (++sp > (1u << 22)) break; }
;             __builtin_amdgcn_fence(__ATOMIC_ACQUIRE, "agent");
;         }
;         asm volatile("s_waitcnt vmcnt(0) lgkmcnt(0)" ::: "memory"); __builtin_amdgcn_s_barrier(); asm volatile("" ::: "memory");
;         if (lane < 32) {
;             const float* slot = xbuf + (size_t)(pmg * BM + row) * 4; float t = 0.f;
; #pragma unroll
;             for (int k = 0; k < 4; ++k) t += __hip_atomic_load(slot + k, __ATOMIC_RELAXED, __HIP_MEMORY_SCOPE_AGENT);
;             S[row] = rsqrtf(t * (1.0f / 1024.0f) + eps);
;         }
.LBB0_808:
	s_or_b64 exec, exec, s[48:49]
	s_mov_b64 s[10:11], exec
	s_andn2_b64 vcc, exec, s[50:51]
	s_cbranch_vccnz .LBB0_735
	s_lshl_b32 s18, s59, 8
	v_add_u32_e32 v204, s18, v195
	v_ashrrev_i32_e32 v205, 31, v204
	v_lshl_add_u64 v[204:205], v[204:205], 4, s[6:7]
	v_lshlrev_b32_e32 v206, 2, v195
	s_mov_b32 s18, 0x40000
.Lpss_b0_poll:
	global_load_dwordx4 v[128:131], v[204:205], off offset:0 sc1
	global_load_dwordx4 v[132:135], v[204:205], off offset:1024 sc1
	s_waitcnt vmcnt(0)
	v_min3_f32 v207, v128, v129, v130
	v_min3_f32 v207, v207, v131, v132
	v_min3_f32 v207, v207, v133, v134
	v_min_f32_e32 v207, v207, v135
	v_cmp_gt_f32_e32 vcc, 0, v207
	s_cbranch_vccz .Lpss_b0_ok
	s_sleep 1
	s_sub_u32 s18, s18, 1
	s_cmp_lg_u32 s18, 0
	s_cbranch_scc1 .Lpss_b0_poll
.Lpss_b0_ok:
	v_add_f32_e32 v128, 0, v128
	v_add_f32_e32 v128, v128, v129
	v_add_f32_e32 v128, v128, v130
	v_add_f32_e32 v128, v128, v131
	v_fmamk_f32 v128, v128, 0x3a800000, v184
	v_mul_f32_e32 v129, 0x4b800000, v128
	v_cmp_gt_f32_e32 vcc, s67, v128
	s_nop 1
	v_cndmask_b32_e32 v128, v128, v129, vcc
	v_rsq_f32_e32 v128, v128
	s_nop 0
	v_mul_f32_e32 v129, 0x45800000, v128
	v_cndmask_b32_e32 v128, v128, v129, vcc
	ds_write_b32 v206, v128 offset:4096
	v_add_f32_e32 v132, 0, v132
	v_add_f32_e32 v132, v132, v133
	v_add_f32_e32 v132, v132, v134
	v_add_f32_e32 v132, v132, v135
	v_fmamk_f32 v132, v132, 0x3a800000, v184
	v_mul_f32_e32 v133, 0x4b800000, v132
	v_cmp_gt_f32_e32 vcc, s67, v132
	s_nop 1
	v_cndmask_b32_e32 v132, v132, v133, vcc
	v_rsq_f32_e32 v132, v132
	s_nop 0
	v_mul_f32_e32 v133, 0x45800000, v132
	v_cndmask_b32_e32 v132, v132, v133, vcc
	ds_write_b32 v206, v132 offset:4352
	s_mov_b32 s18, 0x40000
.Lpss_b1_poll:
	global_load_dwordx4 v[128:131], v[204:205], off offset:2048 sc1
	global_load_dwordx4 v[132:135], v[204:205], off offset:3072 sc1
	s_waitcnt vmcnt(0)
	v_min3_f32 v207, v128, v129, v130
	v_min3_f32 v207, v207, v131, v132
	v_min3_f32 v207, v207, v133, v134
	v_min_f32_e32 v207, v207, v135
	v_cmp_gt_f32_e32 vcc, 0, v207
	s_cbranch_vccz .Lpss_b1_ok
	s_sleep 1
	s_sub_u32 s18, s18, 1
	s_cmp_lg_u32 s18, 0
	s_cbranch_scc1 .Lpss_b1_poll
.Lpss_b1_ok:
	v_add_f32_e32 v128, 0, v128
	v_add_f32_e32 v128, v128, v129
	v_add_f32_e32 v128, v128, v130
	v_add_f32_e32 v128, v128, v131
	v_fmamk_f32 v128, v128, 0x3a800000, v184
	v_mul_f32_e32 v129, 0x4b800000, v128
	v_cmp_gt_f32_e32 vcc, s67, v128
	s_nop 1
	v_cndmask_b32_e32 v128, v128, v129, vcc
	v_rsq_f32_e32 v128, v128
	s_nop 0
	v_mul_f32_e32 v129, 0x45800000, v128
	v_cndmask_b32_e32 v128, v128, v129, vcc
	ds_write_b32 v206, v128 offset:4608
	v_add_f32_e32 v132, 0, v132
	v_add_f32_e32 v132, v132, v133
	v_add_f32_e32 v132, v132, v134
	v_add_f32_e32 v132, v132, v135
	v_fmamk_f32 v132, v132, 0x3a800000, v184
	v_mul_f32_e32 v133, 0x4b800000, v132
	v_cmp_gt_f32_e32 vcc, s67, v132
	s_nop 1
	v_cndmask_b32_e32 v132, v132, v133, vcc
	v_rsq_f32_e32 v132, v132
	s_nop 0
	v_mul_f32_e32 v133, 0x45800000, v132
	v_cndmask_b32_e32 v132, v132, v133, vcc
	ds_write_b32 v206, v132 offset:4864
	s_branch .LBB0_735

; #define PG8_LAS __attribute__((address_space(3)))
;     __device__ __forceinline__ void run(const f32x4 (&v)[2][2][4][2], const Unit& u, int wr, int wc, int fr, int fq, PG8_LAS unsigned char* lds, int wid, int lane) const {
;     ...
;         const int row = wid * 32 + (lane & 31);
;         if (lane < 32) {
;             const float tot = (P[row * 4 + 0] + P[row * 4 + 1]) + (P[row * 4 + 2] + P[row * 4 + 3]);
;             __hip_atomic_store(xbuf + ((size_t)(pmg * BM + row) * 4 + u.pn), tot, __ATOMIC_RELAXED, __HIP_MEMORY_SCOPE_AGENT);
;         }
;         asm volatile("s_waitcnt vmcnt(0)" ::: "memory");
;         if (lane == 0) __hip_atomic_fetch_add(cnt + 64 * pmg, 1u, __ATOMIC_RELAXED, __HIP_MEMORY_SCOPE_AGENT);
;         if (wid == 0) {
;             unsigned sp = 0;
;             while ((unsigned)__builtin_amdgcn_readfirstlane(__hip_atomic_load(cnt + 64 * pmg, __ATOMIC_RELAXED, __HIP_MEMORY_SCOPE_AGENT)) < 32u) { __builtin_amdgcn_s_sleep(2); if (++sp > (1u << 22)) break; }
;             __builtin_amdgcn_fence(__ATOMIC_ACQUIRE, "agent");
;         }
;         asm volatile("s_waitcnt vmcnt(0) lgkmcnt(0)" ::: "memory"); __builtin_amdgcn_s_barrier(); asm volatile("" ::: "memory");
;         if (lane < 32) {
;             const float* slot = xbuf + (size_t)(pmg * BM + row) * 4; float t = 0.f;
; #pragma unroll
;             for (int k = 0; k < 4; ++k) t += __hip_atomic_load(slot + k, __ATOMIC_RELAXED, __HIP_MEMORY_SCOPE_AGENT);
;             S[row] = rsqrtf(t * (1.0f / 1024.0f) + eps);
;         }
;     __device__ __forceinline__ void fused(f32x4 (&acc)[2][2][4][2], const Unit& u, int wr, int wc, int fr, int fq, PG8_LAS unsigned char* lds, int wid, int lane) const {
;         const PG8_LAS float* S = (const PG8_LAS float*)(lds + 4096);
;         const int col0 = u.pn * BM + wc * 32 + 4 * fq;
;         st.run(acc, u, wr, wc, fr, fq, lds, wid, lane);
;         f32x4 g[2][2];
; #pragma unroll
;         for (int bj = 0; bj < 2; ++bj)
; #pragma unroll
;             for (int n = 0; n < 2; ++n) g[bj][n] = *(const f32x4*)(gv + col0 + bj * HALF + n * 16);
.LBB0_1157:
	s_or_b64 exec, exec, s[10:11]
	s_lshl_b32 s78, s16, 5
	s_lshl_b32 s79, s24, 8
	s_or_b32 s78, s79, s78
	v_lshrrev_b32_e32 v137, 2, v138
	v_and_or_b32 v137, v137, 12, s78
	v_lshlrev_b32_e32 v137, 2, v137
	v_and_b32_e32 v190, 8, v157
	v_sub_u32_e32 v136, v157, v190
	v_lshlrev_b32_e32 v190, 3, v190
	v_lshl_add_u32 v136, v136, 12, v137
	v_add_u32_e32 v136, v136, v190
	s_lshl_b32 s78, s50, 12
	s_add_i32 s78, s51, s78
	s_ashr_i32 s79, s78, 31
	s_lshl_b64 s[78:79], s[78:79], 2
	s_add_u32 s78, s14, s78
	s_addc_u32 s79, s15, s79
	s_add_u32 s78, s78, s22
	s_addc_u32 s79, s79, s23
	v_add_u32_e32 v191, v137, v190
	global_load_dwordx4 v[244:247], v191, s[78:79]
	global_load_dwordx4 v[248:251], v191, s[78:79] offset:512
	s_lshl_b32 s78, s50, 14
	s_lshl_b32 s76, s53, 8
	s_add_i32 s76, s76, s78
	s_mov_b32 s77, 0
	s_lshl_b64 s[76:77], s[76:77], 12
	s_add_u32 s76, s12, s76
	s_addc_u32 s77, s13, s77
	v_mov_b32_e32 v192, v136
	v_add_u32_e32 v193, 0x8000, v136
	global_load_dwordx4 v[158:161], v192, s[76:77] nt
	global_load_dwordx4 v[162:165], v193, s[76:77] nt
	v_mov_b32_e32 v192, v136
	v_add_u32_e32 v193, 0x8000, v136
	global_load_dwordx4 v[166:169], v192, s[76:77] offset:512 nt
	global_load_dwordx4 v[170:173], v193, s[76:77] offset:512 nt
	v_add_u32_e32 v192, 0x10000, v136
	v_add_u32_e32 v193, 0x18000, v136
	global_load_dwordx4 v[174:177], v192, s[76:77] nt
	global_load_dwordx4 v[178:181], v193, s[76:77] nt
	v_add_u32_e32 v192, 0x10000, v136
	v_add_u32_e32 v193, 0x18000, v136
	global_load_dwordx4 v[182:185], v192, s[76:77] offset:512 nt
	global_load_dwordx4 v[186:189], v193, s[76:77] offset:512 nt
	v_add_u32_e32 v192, 0x20000, v136
	v_add_u32_e32 v193, 0x28000, v136
	global_load_dwordx4 v[196:199], v192, s[76:77] nt
	global_load_dwordx4 v[200:203], v193, s[76:77] nt
	v_add_u32_e32 v192, 0x20000, v136
	v_add_u32_e32 v193, 0x28000, v136
	global_load_dwordx4 v[204:207], v192, s[76:77] offset:512 nt
	global_load_dwordx4 v[208:211], v193, s[76:77] offset:512 nt
	v_add_u32_e32 v192, 0x30000, v136
	v_add_u32_e32 v193, 0x38000, v136
	global_load_dwordx4 v[212:215], v192, s[76:77] nt
	global_load_dwordx4 v[216:219], v193, s[76:77] nt
	v_add_u32_e32 v192, 0x30000, v136
	v_add_u32_e32 v193, 0x38000, v136
	global_load_dwordx4 v[220:223], v192, s[76:77] offset:512 nt
	global_load_dwordx4 v[224:227], v193, s[76:77] offset:512 nt
	s_mov_b64 s[10:11], exec
	s_cmp_gt_u32 s52, 63
	s_cbranch_scc1 .LBB0_1113
	s_lshl_b32 s25, s28, 8
	v_add_u32_e32 v136, s25, v195
	v_ashrrev_i32_e32 v137, 31, v136
	v_lshl_add_u64 v[136:137], v[136:137], 4, s[8:9]
	v_lshlrev_b32_e32 v190, 2, v195
	s_mov_b32 s25, 0x40000
.Lpss_c0_poll:
	global_load_dwordx4 v[128:131], v[136:137], off offset:0 sc1
	global_load_dwordx4 v[132:135], v[136:137], off offset:1024 sc1
	s_waitcnt vmcnt(0)
	v_min3_f32 v191, v128, v129, v130
	v_min3_f32 v191, v191, v131, v132
	v_min3_f32 v191, v191, v133, v134
	v_min_f32_e32 v191, v191, v135
	v_cmp_gt_f32_e32 vcc, 0, v191
	s_cbranch_vccz .Lpss_c0_ok
	s_sleep 1
	s_sub_u32 s25, s25, 1
	s_cmp_lg_u32 s25, 0
	s_cbranch_scc1 .Lpss_c0_poll
.Lpss_c0_ok:
	v_add_f32_e32 v128, 0, v128
	v_add_f32_e32 v128, v128, v129
	v_add_f32_e32 v128, v128, v130
	v_add_f32_e32 v128, v128, v131
	v_fmamk_f32 v128, v128, 0x3a800000, v154
	v_mul_f32_e32 v129, 0x4b800000, v128
	v_cmp_gt_f32_e32 vcc, s48, v128
	s_nop 1
	v_cndmask_b32_e32 v128, v128, v129, vcc
	v_rsq_f32_e32 v128, v128
	s_nop 0
	v_mul_f32_e32 v129, 0x45800000, v128
	v_cndmask_b32_e32 v128, v128, v129, vcc
	ds_write_b32 v190, v128 offset:4096
	v_add_f32_e32 v132, 0, v132
	v_add_f32_e32 v132, v132, v133
	v_add_f32_e32 v132, v132, v134
	v_add_f32_e32 v132, v132, v135
	v_fmamk_f32 v132, v132, 0x3a800000, v154
	v_mul_f32_e32 v133, 0x4b800000, v132
	v_cmp_gt_f32_e32 vcc, s48, v132
	s_nop 1
	v_cndmask_b32_e32 v132, v132, v133, vcc
	v_rsq_f32_e32 v132, v132
	s_nop 0
	v_mul_f32_e32 v133, 0x45800000, v132
	v_cndmask_b32_e32 v132, v132, v133, vcc
	ds_write_b32 v190, v132 offset:4352
	s_mov_b32 s25, 0x40000
.Lpss_c1_poll:
	global_load_dwordx4 v[128:131], v[136:137], off offset:2048 sc1
	global_load_dwordx4 v[132:135], v[136:137], off offset:3072 sc1
	s_waitcnt vmcnt(0)
	v_min3_f32 v191, v128, v129, v130
	v_min3_f32 v191, v191, v131, v132
	v_min3_f32 v191, v191, v133, v134
	v_min_f32_e32 v191, v191, v135
	v_cmp_gt_f32_e32 vcc, 0, v191
	s_cbranch_vccz .Lpss_c1_ok
	s_sleep 1
	s_sub_u32 s25, s25, 1
	s_cmp_lg_u32 s25, 0
	s_cbranch_scc1 .Lpss_c1_poll
.Lpss_c1_ok:
	v_add_f32_e32 v128, 0, v128
	v_add_f32_e32 v128, v128, v129
	v_add_f32_e32 v128, v128, v130
	v_add_f32_e32 v128, v128, v131
	v_fmamk_f32 v128, v128, 0x3a800000, v154
	v_mul_f32_e32 v129, 0x4b800000, v128
	v_cmp_gt_f32_e32 vcc, s48, v128
	s_nop 1
	v_cndmask_b32_e32 v128, v128, v129, vcc
	v_rsq_f32_e32 v128, v128
	s_nop 0
	v_mul_f32_e32 v129, 0x45800000, v128
	v_cndmask_b32_e32 v128, v128, v129, vcc
	ds_write_b32 v190, v128 offset:4608
	v_add_f32_e32 v132, 0, v132
	v_add_f32_e32 v132, v132, v133
	v_add_f32_e32 v132, v132, v134
	v_add_f32_e32 v132, v132, v135
	v_fmamk_f32 v132, v132, 0x3a800000, v154
	v_mul_f32_e32 v133, 0x4b800000, v132
	v_cmp_gt_f32_e32 vcc, s48, v132
	s_nop 1
	v_cndmask_b32_e32 v132, v132, v133, vcc
	v_rsq_f32_e32 v132, v132
	s_nop 0
	v_mul_f32_e32 v133, 0x45800000, v132
	v_cndmask_b32_e32 v132, v132, v133, vcc
	ds_write_b32 v190, v132 offset:4864
	s_branch .LBB0_1113
